# E-phase loop software-pipelined (next token loads in flight during compute); A-matrix section caches repeated LDS scalars in registers
# speedup vs baseline: 1.0072x; 1.0072x over previous
.Lxi_done:
	v_lshrrev_b32_e32 v58, 4, v94
	v_lshl_or_b32 v109, v58, 2, v0
	v_lshl_add_u32 v112, v40, 2, v95
	v_cmp_ge_u32_e64 s[2:3], v109, v40
	v_mov_b32_e32 v0, 0
	v_lshl_add_u32 v110, v109, 2, v95
	v_mov_b32_e32 v113, 0
	s_barrier
	ds_read_b32 v212, v110 offset:52224
	ds_read_b32 v213, v112 offset:52224
	ds_read_b32 v214, v110 offset:52736
	s_waitcnt lgkmcnt(0)
	s_and_saveexec_b64 s[4:5], s[2:3]
	s_cbranch_execz .LBB0_990
	v_mov_b32_e32 v111, v212
	v_mov_b32_e32 v113, v213
	v_sub_f32_e32 v111, v111, v113
	v_mul_f32_e32 v111, 0x3fb8aa3b, v111
	v_exp_f32_e32 v113, v111
.LBB0_990:
	s_or_b64 exec, exec, s[4:5]
	v_cmp_gt_u32_e64 s[4:5], v109, v40
	s_and_saveexec_b64 s[44:45], s[4:5]
	s_cbranch_execz .LBB0_992
	v_mov_b32_e32 v0, v214
	v_mul_f32_e32 v0, v30, v0
	v_mul_f32_e32 v0, v113, v0
.LBB0_992:
	s_or_b64 exec, exec, s[44:45]
	v_lshlrev_b32_e32 v111, 1, v40
	v_and_b32_e32 v116, 24, v111
	v_lshlrev_b32_e32 v114, 8, v109
	v_lshlrev_b32_e32 v111, 2, v40
	v_add3_u32 v118, v174, v114, v111
	v_and_or_b32 v125, v175, 3, v116
	v_lshlrev_b32_e32 v115, 6, v109
	ds_write_b32 v118, v0 offset:18432
	v_mul_f32_e32 v0, v26, v113
	s_mov_b64 s[4:5], 0x14a94000
	v_cvt_pk_bf16_f32 v113, v0, s0
	v_or_b32_e32 v0, v115, v125
	v_lshl_add_u64 v[36:37], v[36:37], 0, s[4:5]
	v_lshlrev_b32_e32 v0, 1, v0
	v_lshl_add_u64 v[120:121], v[36:37], 0, v[0:1]
	v_or_b32_e32 v119, 1, v109
	global_store_short v[120:121], v113, off
	v_cmp_ge_u32_e64 s[4:5], v119, v40
	v_mov_b32_e32 v0, 0
	v_mov_b32_e32 v113, 0
	ds_read_b32 v215, v110 offset:52228
	ds_read_b32 v216, v110 offset:52740
	s_waitcnt lgkmcnt(0)
	s_and_saveexec_b64 s[44:45], s[4:5]
	s_cbranch_execz .LBB0_994
	v_mov_b32_e32 v113, v215
	v_mov_b32_e32 v114, v213
	v_sub_f32_e32 v113, v113, v114
	v_mul_f32_e32 v113, 0x3fb8aa3b, v113
	v_exp_f32_e32 v113, v113
.LBB0_994:
	s_or_b64 exec, exec, s[44:45]
	s_and_saveexec_b64 s[4:5], s[2:3]
	s_cbranch_execz .LBB0_996
	v_mov_b32_e32 v0, v216
	v_mul_f32_e32 v0, v31, v0
	v_mul_f32_e32 v0, v113, v0
.LBB0_996:
	s_or_b64 exec, exec, s[4:5]
	v_lshlrev_b32_e32 v114, 8, v119
	v_add3_u32 v121, v174, v114, v111
	v_lshlrev_b32_e32 v117, 6, v119
	ds_write_b32 v121, v0 offset:18432
	v_mul_f32_e32 v0, v27, v113
	v_cvt_pk_bf16_f32 v113, v0, s0
	v_or_b32_e32 v0, v117, v125
	v_lshlrev_b32_e32 v0, 1, v0
	v_lshl_add_u64 v[122:123], v[36:37], 0, v[0:1]
	global_store_short v[122:123], v113, off
	v_or_b32_e32 v113, 2, v109
	v_cmp_ge_u32_e64 s[2:3], v113, v40
	v_mov_b32_e32 v0, 0
	v_mov_b32_e32 v114, 0
	ds_read_b32 v217, v110 offset:52232
	ds_read_b32 v218, v110 offset:52744
	s_waitcnt lgkmcnt(0)
	s_and_saveexec_b64 s[4:5], s[2:3]
	s_cbranch_execz .LBB0_998
	v_mov_b32_e32 v114, v217
	v_mov_b32_e32 v120, v213
	v_sub_f32_e32 v114, v114, v120
	v_mul_f32_e32 v114, 0x3fb8aa3b, v114
	v_exp_f32_e32 v114, v114
.LBB0_998:
	s_or_b64 exec, exec, s[4:5]
	v_cmp_gt_u32_e64 s[2:3], v113, v40
	s_and_saveexec_b64 s[4:5], s[2:3]
	s_cbranch_execz .LBB0_1000
	v_mov_b32_e32 v0, v218
	v_mul_f32_e32 v0, v32, v0
	v_mul_f32_e32 v0, v114, v0
.LBB0_1000:
	s_or_b64 exec, exec, s[4:5]
	v_lshlrev_b32_e32 v122, 8, v113
	v_add3_u32 v122, v174, v122, v111
	v_lshlrev_b32_e32 v120, 6, v113
	ds_write_b32 v122, v0 offset:18432
	v_mul_f32_e32 v0, v28, v114
	v_cvt_pk_bf16_f32 v114, v0, s0
	v_or_b32_e32 v0, v120, v125
	v_lshlrev_b32_e32 v0, 1, v0
	v_lshl_add_u64 v[126:127], v[36:37], 0, v[0:1]
	global_store_short v[126:127], v114, off
	v_or_b32_e32 v114, 3, v109
	v_cmp_ge_u32_e64 s[2:3], v114, v40
	v_mov_b32_e32 v0, 0
	v_mov_b32_e32 v127, 0
	ds_read_b32 v219, v110 offset:52236
	ds_read_b32 v244, v110 offset:52748
	s_waitcnt lgkmcnt(0)
	s_and_saveexec_b64 s[4:5], s[2:3]
	s_cbranch_execz .LBB0_1002
	v_mov_b32_e32 v123, v219
	v_mov_b32_e32 v124, v213
	v_sub_f32_e32 v123, v123, v124
	v_mul_f32_e32 v123, 0x3fb8aa3b, v123
	v_exp_f32_e32 v127, v123
.LBB0_1002:
	s_or_b64 exec, exec, s[4:5]
	v_cmp_gt_u32_e64 s[2:3], v114, v40
	s_and_saveexec_b64 s[4:5], s[2:3]
	s_cbranch_execz .LBB0_1004
	v_mov_b32_e32 v0, v244
	v_mul_f32_e32 v0, v33, v0
	v_mul_f32_e32 v0, v127, v0
.LBB0_1004:
	s_or_b64 exec, exec, s[4:5]
	v_lshlrev_b32_e32 v124, 8, v114
	v_add3_u32 v124, v174, v124, v111
	v_lshlrev_b32_e32 v123, 6, v114
	ds_write_b32 v124, v0 offset:18432
	v_mul_f32_e32 v0, v29, v127
	v_cvt_pk_bf16_f32 v127, v0, s0
	v_or_b32_e32 v0, v123, v125
	v_lshlrev_b32_e32 v0, 1, v0
	v_lshl_add_u64 v[128:129], v[36:37], 0, v[0:1]
	global_store_short v[128:129], v127, off
	v_or_b32_e32 v126, 16, v40
	v_cmp_ge_u32_e64 s[2:3], v109, v126
	v_mov_b32_e32 v0, 0
	v_mov_b32_e32 v128, 0
	ds_read_b32 v245, v112 offset:52288
	s_waitcnt lgkmcnt(0)
	s_and_saveexec_b64 s[4:5], s[2:3]
	s_cbranch_execz .LBB0_1006
	v_mov_b32_e32 v127, v212
	v_mov_b32_e32 v128, v245
	v_sub_f32_e32 v127, v127, v128
	v_mul_f32_e32 v127, 0x3fb8aa3b, v127
	v_exp_f32_e32 v128, v127
.LBB0_1006:
	s_or_b64 exec, exec, s[4:5]
	v_cmp_gt_u32_e64 s[4:5], v109, v126
	s_and_saveexec_b64 s[44:45], s[4:5]
	s_cbranch_execz .LBB0_1008
	v_mov_b32_e32 v0, v214
	v_mul_f32_e32 v0, v22, v0
	v_mul_f32_e32 v0, v128, v0
.LBB0_1008:
	s_or_b64 exec, exec, s[44:45]
	v_or_b32_e32 v127, 4, v125
	ds_write_b32 v118, v0 offset:18496
	v_mul_f32_e32 v0, v18, v128
	v_cvt_pk_bf16_f32 v125, v0, s0
	v_or_b32_e32 v0, v127, v115
	v_lshlrev_b32_e32 v0, 1, v0
	v_lshl_add_u64 v[128:129], v[36:37], 0, v[0:1]
	global_store_short v[128:129], v125, off
	v_cmp_ge_u32_e64 s[4:5], v119, v126
	v_mov_b32_e32 v0, 0
	v_mov_b32_e32 v125, 0
	s_and_saveexec_b64 s[44:45], s[4:5]
	s_cbranch_execz .LBB0_1010
	v_mov_b32_e32 v125, v215
	v_mov_b32_e32 v128, v245
	v_sub_f32_e32 v125, v125, v128
	v_mul_f32_e32 v125, 0x3fb8aa3b, v125
	v_exp_f32_e32 v125, v125
.LBB0_1010:
	s_or_b64 exec, exec, s[44:45]
	s_and_saveexec_b64 s[4:5], s[2:3]
	s_cbranch_execz .LBB0_1012
	v_mov_b32_e32 v0, v216
	v_mul_f32_e32 v0, v23, v0
	v_mul_f32_e32 v0, v125, v0
.LBB0_1012:
	s_or_b64 exec, exec, s[4:5]
	ds_write_b32 v121, v0 offset:18496
	v_mul_f32_e32 v0, v19, v125
	v_cvt_pk_bf16_f32 v125, v0, s0
	v_or_b32_e32 v0, v117, v127
	v_lshlrev_b32_e32 v0, 1, v0
	v_lshl_add_u64 v[128:129], v[36:37], 0, v[0:1]
	global_store_short v[128:129], v125, off
	v_cmp_ge_u32_e64 s[2:3], v113, v126
	v_mov_b32_e32 v0, 0
	v_mov_b32_e32 v125, 0
	s_and_saveexec_b64 s[4:5], s[2:3]
	s_cbranch_execz .LBB0_1014
	v_mov_b32_e32 v125, v217
	v_mov_b32_e32 v128, v245
	v_sub_f32_e32 v125, v125, v128
	v_mul_f32_e32 v125, 0x3fb8aa3b, v125
	v_exp_f32_e32 v125, v125
.LBB0_1014:
	s_or_b64 exec, exec, s[4:5]
	v_cmp_gt_u32_e64 s[2:3], v113, v126
	s_and_saveexec_b64 s[4:5], s[2:3]
	s_cbranch_execz .LBB0_1016
	v_mov_b32_e32 v0, v218
	v_mul_f32_e32 v0, v24, v0
	v_mul_f32_e32 v0, v125, v0
.LBB0_1016:
	s_or_b64 exec, exec, s[4:5]
	ds_write_b32 v122, v0 offset:18496
	v_mul_f32_e32 v0, v20, v125
	v_cvt_pk_bf16_f32 v125, v0, s0
	v_or_b32_e32 v0, v120, v127
	v_lshlrev_b32_e32 v0, 1, v0
	v_lshl_add_u64 v[128:129], v[36:37], 0, v[0:1]
	global_store_short v[128:129], v125, off
	v_cmp_ge_u32_e64 s[2:3], v114, v126
	v_mov_b32_e32 v0, 0
	v_mov_b32_e32 v128, 0
	s_and_saveexec_b64 s[4:5], s[2:3]
	s_cbranch_execz .LBB0_1018
	v_mov_b32_e32 v125, v219
	v_mov_b32_e32 v128, v245
	v_sub_f32_e32 v125, v125, v128
	v_mul_f32_e32 v125, 0x3fb8aa3b, v125
	v_exp_f32_e32 v128, v125
.LBB0_1018:
	s_or_b64 exec, exec, s[4:5]
	v_cmp_gt_u32_e64 s[2:3], v114, v126
	s_and_saveexec_b64 s[4:5], s[2:3]
	s_cbranch_execz .LBB0_1020
	v_mov_b32_e32 v0, v244
	v_mul_f32_e32 v0, v25, v0
	v_mul_f32_e32 v0, v128, v0
.LBB0_1020:
	s_or_b64 exec, exec, s[4:5]
	ds_write_b32 v124, v0 offset:18496
	v_mul_f32_e32 v0, v21, v128
	v_cvt_pk_bf16_f32 v128, v0, s0
	v_or_b32_e32 v0, v123, v127
	v_lshlrev_b32_e32 v0, 1, v0
	v_lshl_add_u64 v[126:127], v[36:37], 0, v[0:1]
	global_store_short v[126:127], v128, off
	v_or_b32_e32 v125, 32, v40
	v_cmp_ge_u32_e64 s[2:3], v109, v125
	v_mov_b32_e32 v0, 0
	v_mov_b32_e32 v127, 0
	ds_read_b32 v246, v112 offset:52352
	s_waitcnt lgkmcnt(0)
	s_and_saveexec_b64 s[4:5], s[2:3]
	s_cbranch_execz .LBB0_1022
	v_mov_b32_e32 v126, v212
	v_mov_b32_e32 v127, v246
	v_sub_f32_e32 v126, v126, v127
	v_mul_f32_e32 v126, 0x3fb8aa3b, v126
	v_exp_f32_e32 v127, v126
.LBB0_1022:
	s_or_b64 exec, exec, s[4:5]
	v_cmp_gt_u32_e64 s[4:5], v109, v125
	s_and_saveexec_b64 s[44:45], s[4:5]
	s_cbranch_execz .LBB0_1024
	v_mov_b32_e32 v0, v214
	v_mul_f32_e32 v0, v14, v0
	v_mul_f32_e32 v0, v127, v0
.LBB0_1024:
	s_or_b64 exec, exec, s[44:45]
	v_and_or_b32 v126, v125, 35, v116
	ds_write_b32 v118, v0 offset:18560
	v_mul_f32_e32 v0, v10, v127
	v_cvt_pk_bf16_f32 v127, v0, s0
	v_or_b32_e32 v0, v115, v126
	v_lshlrev_b32_e32 v0, 1, v0
	v_lshl_add_u64 v[128:129], v[36:37], 0, v[0:1]
	global_store_short v[128:129], v127, off
	v_cmp_ge_u32_e64 s[4:5], v119, v125
	v_mov_b32_e32 v0, 0
	v_mov_b32_e32 v127, 0
	s_and_saveexec_b64 s[44:45], s[4:5]
	s_cbranch_execz .LBB0_1026
	v_mov_b32_e32 v127, v215
	v_mov_b32_e32 v128, v246
	v_sub_f32_e32 v127, v127, v128
	v_mul_f32_e32 v127, 0x3fb8aa3b, v127
	v_exp_f32_e32 v127, v127
.LBB0_1026:
	s_or_b64 exec, exec, s[44:45]
	s_and_saveexec_b64 s[4:5], s[2:3]
	s_cbranch_execz .LBB0_1028
	v_mov_b32_e32 v0, v216
	v_mul_f32_e32 v0, v15, v0
	v_mul_f32_e32 v0, v127, v0
.LBB0_1028:
	s_or_b64 exec, exec, s[4:5]
	ds_write_b32 v121, v0 offset:18560
	v_mul_f32_e32 v0, v11, v127
	v_cvt_pk_bf16_f32 v127, v0, s0
	v_or_b32_e32 v0, v117, v126
	v_lshlrev_b32_e32 v0, 1, v0
	v_lshl_add_u64 v[128:129], v[36:37], 0, v[0:1]
	global_store_short v[128:129], v127, off
	v_cmp_ge_u32_e64 s[2:3], v113, v125
	v_mov_b32_e32 v0, 0
	v_mov_b32_e32 v127, 0
	s_and_saveexec_b64 s[4:5], s[2:3]
	s_cbranch_execz .LBB0_1030
	v_mov_b32_e32 v127, v217
	v_mov_b32_e32 v128, v246
	v_sub_f32_e32 v127, v127, v128
	v_mul_f32_e32 v127, 0x3fb8aa3b, v127
	v_exp_f32_e32 v127, v127
.LBB0_1030:
	s_or_b64 exec, exec, s[4:5]
	v_cmp_gt_u32_e64 s[2:3], v113, v125
	s_and_saveexec_b64 s[4:5], s[2:3]
	s_cbranch_execz .LBB0_1032
	v_mov_b32_e32 v0, v218
	v_mul_f32_e32 v0, v16, v0
	v_mul_f32_e32 v0, v127, v0
.LBB0_1032:
	s_or_b64 exec, exec, s[4:5]
	ds_write_b32 v122, v0 offset:18560
	v_mul_f32_e32 v0, v12, v127
	v_cvt_pk_bf16_f32 v127, v0, s0
	v_or_b32_e32 v0, v120, v126
	v_lshlrev_b32_e32 v0, 1, v0
	v_lshl_add_u64 v[128:129], v[36:37], 0, v[0:1]
	global_store_short v[128:129], v127, off
	v_cmp_ge_u32_e64 s[2:3], v114, v125
	v_mov_b32_e32 v0, 0
	v_mov_b32_e32 v127, 0
	s_and_saveexec_b64 s[4:5], s[2:3]
	s_cbranch_execz .LBB0_1034
	v_mov_b32_e32 v127, v219
	v_mov_b32_e32 v128, v246
	v_sub_f32_e32 v127, v127, v128
	v_mul_f32_e32 v127, 0x3fb8aa3b, v127
	v_exp_f32_e32 v127, v127
.LBB0_1034:
	s_or_b64 exec, exec, s[4:5]
	v_cmp_gt_u32_e64 s[2:3], v114, v125
	s_and_saveexec_b64 s[4:5], s[2:3]
	s_cbranch_execz .LBB0_1036
	v_mov_b32_e32 v0, v244
	v_mul_f32_e32 v0, v17, v0
	v_mul_f32_e32 v0, v127, v0
.LBB0_1036:
	s_or_b64 exec, exec, s[4:5]
	ds_write_b32 v124, v0 offset:18560
	v_mul_f32_e32 v0, v13, v127
	v_cvt_pk_bf16_f32 v128, v0, s0
	v_or_b32_e32 v0, v123, v126
	v_lshlrev_b32_e32 v0, 1, v0
	v_lshl_add_u64 v[126:127], v[36:37], 0, v[0:1]
	global_store_short v[126:127], v128, off
	v_or_b32_e32 v125, 48, v40
	v_cmp_ge_u32_e64 s[2:3], v109, v125
	v_mov_b32_e32 v0, 0
	v_mov_b32_e32 v126, 0
	ds_read_b32 v247, v112 offset:52416
	s_waitcnt lgkmcnt(0)
	s_and_saveexec_b64 s[4:5], s[2:3]
	s_cbranch_execz .LBB0_1038
	v_mov_b32_e32 v126, v212
	v_mov_b32_e32 v127, v247
	v_sub_f32_e32 v126, v126, v127
	v_mul_f32_e32 v126, 0x3fb8aa3b, v126
	v_exp_f32_e32 v126, v126
.LBB0_1038:
	s_or_b64 exec, exec, s[4:5]
	v_cmp_gt_u32_e64 s[4:5], v109, v125
	s_and_saveexec_b64 s[44:45], s[4:5]
	s_cbranch_execz .LBB0_1040
	v_mov_b32_e32 v0, v214
	v_mul_f32_e32 v0, v6, v0
	v_mul_f32_e32 v0, v126, v0
.LBB0_1040:
	s_or_b64 exec, exec, s[44:45]
	v_and_b32_e32 v127, 35, v125
	v_or3_b32 v116, v127, v116, 4
	ds_write_b32 v118, v0 offset:18624
	v_mul_f32_e32 v0, v2, v126
	v_cvt_pk_bf16_f32 v118, v0, s0
	v_or_b32_e32 v0, v116, v115
	v_lshlrev_b32_e32 v0, 1, v0
	v_lshl_add_u64 v[126:127], v[36:37], 0, v[0:1]
	v_cmp_ge_u32_e64 s[4:5], v119, v125
	v_mov_b32_e32 v0, 0
	v_mov_b32_e32 v115, 0
	global_store_short v[126:127], v118, off
	s_and_saveexec_b64 s[44:45], s[4:5]
	s_cbranch_execz .LBB0_1042
	v_mov_b32_e32 v115, v215
	v_mov_b32_e32 v118, v247
	v_sub_f32_e32 v115, v115, v118
	v_mul_f32_e32 v115, 0x3fb8aa3b, v115
	v_exp_f32_e32 v115, v115
.LBB0_1042:
	s_or_b64 exec, exec, s[44:45]
	s_and_saveexec_b64 s[4:5], s[2:3]
	s_cbranch_execz .LBB0_1044
	v_mov_b32_e32 v0, v216
	v_mul_f32_e32 v0, v7, v0
	v_mul_f32_e32 v0, v115, v0
.LBB0_1044:
	s_or_b64 exec, exec, s[4:5]
	ds_write_b32 v121, v0 offset:18624
	v_mul_f32_e32 v0, v3, v115
	v_cvt_pk_bf16_f32 v115, v0, s0
	v_or_b32_e32 v0, v117, v116
	v_lshlrev_b32_e32 v0, 1, v0
	v_lshl_add_u64 v[118:119], v[36:37], 0, v[0:1]
	global_store_short v[118:119], v115, off
	v_cmp_ge_u32_e64 s[2:3], v113, v125
	v_mov_b32_e32 v0, 0
	v_mov_b32_e32 v115, 0
	s_and_saveexec_b64 s[4:5], s[2:3]
	s_cbranch_execz .LBB0_1046
	v_mov_b32_e32 v115, v217
	v_mov_b32_e32 v117, v247
	v_sub_f32_e32 v115, v115, v117
	v_mul_f32_e32 v115, 0x3fb8aa3b, v115
	v_exp_f32_e32 v115, v115
.LBB0_1046:
	s_or_b64 exec, exec, s[4:5]
	v_cmp_gt_u32_e64 s[2:3], v113, v125
	s_and_saveexec_b64 s[4:5], s[2:3]
	s_cbranch_execz .LBB0_1048
	v_mov_b32_e32 v0, v218
	v_mul_f32_e32 v0, v8, v0
	v_mul_f32_e32 v0, v115, v0
.LBB0_1048:
	s_or_b64 exec, exec, s[4:5]
	ds_write_b32 v122, v0 offset:18624
	v_mul_f32_e32 v0, v4, v115
	v_cvt_pk_bf16_f32 v113, v0, s0
	v_or_b32_e32 v0, v120, v116
	v_lshlrev_b32_e32 v0, 1, v0
	v_lshl_add_u64 v[118:119], v[36:37], 0, v[0:1]
	global_store_short v[118:119], v113, off
	v_cmp_ge_u32_e64 s[2:3], v114, v125
	v_mov_b32_e32 v0, 0
	v_mov_b32_e32 v113, 0
	s_and_saveexec_b64 s[4:5], s[2:3]
	s_cbranch_execz .LBB0_1050
	v_mov_b32_e32 v113, v219
	v_mov_b32_e32 v112, v247
	v_sub_f32_e32 v112, v113, v112
	v_mul_f32_e32 v112, 0x3fb8aa3b, v112
	v_exp_f32_e32 v113, v112
.LBB0_1050:
	s_or_b64 exec, exec, s[4:5]
	v_cmp_gt_u32_e64 s[2:3], v114, v125
	s_and_saveexec_b64 s[4:5], s[2:3]
	s_cbranch_execz .LBB0_1052
	v_mov_b32_e32 v0, v244
	v_mul_f32_e32 v0, v9, v0
	v_mul_f32_e32 v0, v113, v0

.LBB0_1066:
	s_or_b64 exec, exec, s[2:3]
	v_lshlrev_b32_e32 v32, 6, v27
	v_mul_f32_e32 v0, v28, v0
	v_cvt_pk_bf16_f32 v28, v0, s0
	v_or_b32_e32 v0, v32, v118
	v_lshlrev_b32_e32 v0, 1, v0
	v_lshl_add_u32 v117, v27, 8, v174
	v_lshl_add_u64 v[122:123], v[34:35], 0, v[0:1]
	v_lshl_add_u32 v109, v119, 2, v117
	global_store_short v[122:123], v28, off
	v_cmp_ge_u32_e64 s[2:3], v37, v116
	v_lshl_add_u32 v28, v37, 2, v95
	ds_write_b32 v109, v121 offset:35068
	ds_read_b32 v248, v28 offset:52480
	ds_read_b32 v249, v110 offset:52672
	ds_read_b32 v250, v28 offset:52992
	s_waitcnt lgkmcnt(0)
	s_and_saveexec_b64 s[4:5], s[2:3]
	s_cbranch_execz .LBB0_1068
	v_mov_b32_e32 v0, v248
	v_mov_b32_e32 v95, v249
	v_sub_f32_e32 v0, v0, v95
	v_mul_f32_e32 v0, 0x3fb8aa3b, v0
	v_exp_f32_e32 v120, v0
.LBB0_1068:
	s_or_b64 exec, exec, s[4:5]
	v_cmp_gt_u32_e64 s[2:3], v37, v116
	v_mov_b32_e32 v121, 0
	v_mov_b32_e32 v0, 0
	s_and_saveexec_b64 s[4:5], s[2:3]
	s_cbranch_execz .LBB0_1070
	v_mov_b32_e32 v0, v250
	v_mul_f32_e32 v0, v33, v0
	v_mul_f32_e32 v0, v120, v0
.LBB0_1070:
	s_or_b64 exec, exec, s[4:5]
	v_lshl_add_u32 v116, v37, 8, v174
	v_lshl_add_u32 v95, v119, 2, v116
	v_lshlrev_b32_e32 v33, 6, v37
	ds_write_b32 v95, v0 offset:35068
	v_mul_f32_e32 v0, v29, v120
	v_cvt_pk_bf16_f32 v29, v0, s0
	v_or_b32_e32 v0, v33, v118
	v_lshlrev_b32_e32 v0, 1, v0
	v_lshl_add_u64 v[118:119], v[34:35], 0, v[0:1]
	global_store_short v[118:119], v29, off
	v_xor_b32_e32 v29, 47, v40
	v_cmp_ge_u32_e64 s[2:3], v112, v29
	ds_read_b32 v251, v28 offset:52492
	ds_read_b32 v212, v110 offset:52608
	ds_read_b32 v214, v28 offset:53004
	s_waitcnt lgkmcnt(0)
	s_and_saveexec_b64 s[4:5], s[2:3]
	s_cbranch_execz .LBB0_1072
	v_mov_b32_e32 v0, v251
	v_mov_b32_e32 v118, v212
	v_sub_f32_e32 v0, v0, v118
	v_mul_f32_e32 v0, 0x3fb8aa3b, v0
	v_exp_f32_e32 v121, v0
.LBB0_1072:
	s_or_b64 exec, exec, s[4:5]
	v_cmp_gt_u32_e64 s[2:3], v112, v29
	v_mov_b32_e32 v119, 0
	v_mov_b32_e32 v0, 0
	s_and_saveexec_b64 s[4:5], s[2:3]
	s_cbranch_execz .LBB0_1074
	v_mov_b32_e32 v0, v214
	v_mul_f32_e32 v0, v22, v0
	v_mul_f32_e32 v0, v121, v0
.LBB0_1074:
	s_or_b64 exec, exec, s[4:5]
	v_lshlrev_b32_e32 v22, 1, v29
	v_and_b32_e32 v118, 35, v29
	v_and_or_b32 v22, v22, 24, v118
	v_or_b32_e32 v118, 0x1000, v36
	v_lshl_add_u32 v114, v118, 2, v114
	ds_write_b32 v114, v0 offset:18560
	v_mul_f32_e32 v0, v18, v121
	v_cvt_pk_bf16_f32 v18, v0, s0
	v_or_b32_e32 v0, v30, v22
	v_lshlrev_b32_e32 v0, 1, v0
	v_lshl_add_u64 v[120:121], v[34:35], 0, v[0:1]
	v_cmp_ge_u32_e64 s[2:3], v26, v29
	global_store_short v[120:121], v18, off
	ds_read_b32 v215, v28 offset:52488
	ds_read_b32 v216, v28 offset:53000
	s_waitcnt lgkmcnt(0)
	s_and_saveexec_b64 s[4:5], s[2:3]
	s_cbranch_execz .LBB0_1076
	v_mov_b32_e32 v0, v215
	v_mov_b32_e32 v18, v212
	v_sub_f32_e32 v0, v0, v18
	v_mul_f32_e32 v0, 0x3fb8aa3b, v0
	v_exp_f32_e32 v119, v0
.LBB0_1076:
	s_or_b64 exec, exec, s[4:5]
	v_cmp_gt_u32_e64 s[2:3], v26, v29
	v_mov_b32_e32 v18, 0
	v_mov_b32_e32 v0, 0
	s_and_saveexec_b64 s[4:5], s[2:3]
	s_cbranch_execz .LBB0_1078
	v_mov_b32_e32 v0, v216
	v_mul_f32_e32 v0, v23, v0
	v_mul_f32_e32 v0, v119, v0
.LBB0_1078:
	s_or_b64 exec, exec, s[4:5]
	v_lshl_add_u32 v23, v118, 2, v115
	ds_write_b32 v23, v0 offset:18560
	v_mul_f32_e32 v0, v19, v119
	v_cvt_pk_bf16_f32 v19, v0, s0
	v_or_b32_e32 v0, v31, v22
	v_lshlrev_b32_e32 v0, 1, v0
	v_lshl_add_u64 v[114:115], v[34:35], 0, v[0:1]
	v_cmp_ge_u32_e64 s[2:3], v27, v29
	global_store_short v[114:115], v19, off
	ds_read_b32 v217, v28 offset:52484
	ds_read_b32 v218, v28 offset:52996
	s_waitcnt lgkmcnt(0)
	s_and_saveexec_b64 s[4:5], s[2:3]
	s_cbranch_execz .LBB0_1080
	v_mov_b32_e32 v0, v217
	v_mov_b32_e32 v18, v212
	v_sub_f32_e32 v0, v0, v18
	v_mul_f32_e32 v0, 0x3fb8aa3b, v0
	v_exp_f32_e32 v18, v0
.LBB0_1080:
	s_or_b64 exec, exec, s[4:5]
	v_cmp_gt_u32_e64 s[2:3], v27, v29
	v_mov_b32_e32 v23, 0
	v_mov_b32_e32 v0, 0
	s_and_saveexec_b64 s[4:5], s[2:3]
	s_cbranch_execz .LBB0_1082
	v_mov_b32_e32 v0, v218
	v_mul_f32_e32 v0, v24, v0
	v_mul_f32_e32 v0, v18, v0
.LBB0_1082:
	s_or_b64 exec, exec, s[4:5]
	v_lshl_add_u32 v19, v118, 2, v117
	ds_write_b32 v19, v0 offset:18560
	v_mul_f32_e32 v0, v20, v18
	v_cvt_pk_bf16_f32 v20, v0, s0
	v_or_b32_e32 v0, v32, v22
	v_lshlrev_b32_e32 v0, 1, v0
	v_lshl_add_u64 v[18:19], v[34:35], 0, v[0:1]
	v_cmp_ge_u32_e64 s[2:3], v37, v29
	global_store_short v[18:19], v20, off
	s_and_saveexec_b64 s[4:5], s[2:3]
	s_cbranch_execz .LBB0_1084
	v_mov_b32_e32 v0, v248
	v_mov_b32_e32 v18, v212
	v_sub_f32_e32 v0, v0, v18
	v_mul_f32_e32 v0, 0x3fb8aa3b, v0
	v_exp_f32_e32 v23, v0
.LBB0_1084:
	s_or_b64 exec, exec, s[4:5]
	v_cmp_gt_u32_e64 s[2:3], v37, v29
	v_mov_b32_e32 v19, 0
	v_mov_b32_e32 v0, 0
	s_and_saveexec_b64 s[4:5], s[2:3]
	s_cbranch_execz .LBB0_1086
	v_mov_b32_e32 v0, v250
	v_mul_f32_e32 v0, v25, v0
	v_mul_f32_e32 v0, v23, v0
.LBB0_1086:
	s_or_b64 exec, exec, s[4:5]
	v_lshl_add_u32 v18, v118, 2, v116
	ds_write_b32 v18, v0 offset:18560
	v_mul_f32_e32 v0, v21, v23
	v_cvt_pk_bf16_f32 v18, v0, s0
	v_or_b32_e32 v0, v33, v22
	v_lshlrev_b32_e32 v0, 1, v0
	v_lshl_add_u64 v[20:21], v[34:35], 0, v[0:1]
	global_store_short v[20:21], v18, off
	v_xor_b32_e32 v18, 31, v40
	v_cmp_ge_u32_e64 s[2:3], v112, v18
	ds_read_b32 v219, v110 offset:52544
	s_waitcnt lgkmcnt(0)
	s_and_saveexec_b64 s[4:5], s[2:3]
	s_cbranch_execz .LBB0_1088
	v_mov_b32_e32 v0, v251
	v_mov_b32_e32 v19, v219
	v_sub_f32_e32 v0, v0, v19
	v_mul_f32_e32 v0, 0x3fb8aa3b, v0
	v_exp_f32_e32 v19, v0
.LBB0_1088:
	s_or_b64 exec, exec, s[4:5]
	v_cmp_gt_u32_e64 s[2:3], v112, v18
	v_mov_b32_e32 v20, 0
	v_mov_b32_e32 v0, 0
	s_and_saveexec_b64 s[4:5], s[2:3]
	s_cbranch_execz .LBB0_1090
	v_mov_b32_e32 v0, v214
	v_mul_f32_e32 v0, v14, v0
	v_mul_f32_e32 v0, v19, v0
.LBB0_1090:
	s_or_b64 exec, exec, s[4:5]
	v_lshlrev_b32_e32 v14, 1, v18
	v_and_b32_e32 v14, 24, v14
	v_and_b32_e32 v21, 3, v18
	v_or3_b32 v14, v21, v14, 4
	ds_write_b32 v111, v0 offset:34940
	v_mul_f32_e32 v0, v10, v19
	v_cvt_pk_bf16_f32 v10, v0, s0
	v_or_b32_e32 v0, v30, v14
	v_lshlrev_b32_e32 v0, 1, v0
	v_lshl_add_u64 v[22:23], v[34:35], 0, v[0:1]
	v_cmp_ge_u32_e64 s[2:3], v26, v18
	global_store_short v[22:23], v10, off
	s_and_saveexec_b64 s[4:5], s[2:3]
	s_cbranch_execz .LBB0_1092
	v_mov_b32_e32 v0, v215
	v_mov_b32_e32 v10, v219
	v_sub_f32_e32 v0, v0, v10
	v_mul_f32_e32 v0, 0x3fb8aa3b, v0
	v_exp_f32_e32 v20, v0
.LBB0_1092:
	s_or_b64 exec, exec, s[4:5]
	v_cmp_gt_u32_e64 s[2:3], v26, v18
	v_mov_b32_e32 v10, 0
	v_mov_b32_e32 v0, 0
	s_and_saveexec_b64 s[4:5], s[2:3]
	s_cbranch_execz .LBB0_1094
	v_mov_b32_e32 v0, v216
	v_mul_f32_e32 v0, v15, v0
	v_mul_f32_e32 v0, v20, v0
.LBB0_1094:
	s_or_b64 exec, exec, s[4:5]
	ds_write_b32 v113, v0 offset:34940
	v_mul_f32_e32 v0, v11, v20
	v_cvt_pk_bf16_f32 v11, v0, s0
	v_or_b32_e32 v0, v31, v14
	v_lshlrev_b32_e32 v0, 1, v0
	v_lshl_add_u64 v[20:21], v[34:35], 0, v[0:1]
	v_cmp_ge_u32_e64 s[2:3], v27, v18
	global_store_short v[20:21], v11, off
	s_and_saveexec_b64 s[4:5], s[2:3]
	s_cbranch_execz .LBB0_1096
	v_mov_b32_e32 v0, v217
	v_mov_b32_e32 v10, v219
	v_sub_f32_e32 v0, v0, v10
	v_mul_f32_e32 v0, 0x3fb8aa3b, v0
	v_exp_f32_e32 v10, v0
.LBB0_1096:
	s_or_b64 exec, exec, s[4:5]
	v_cmp_gt_u32_e64 s[2:3], v27, v18
	v_mov_b32_e32 v11, 0
	v_mov_b32_e32 v0, 0
	s_and_saveexec_b64 s[4:5], s[2:3]
	s_cbranch_execz .LBB0_1098
	v_mov_b32_e32 v0, v218
	v_mul_f32_e32 v0, v16, v0
	v_mul_f32_e32 v0, v10, v0
.LBB0_1098:
	s_or_b64 exec, exec, s[4:5]
	ds_write_b32 v109, v0 offset:34940
	v_mul_f32_e32 v0, v12, v10
	v_cvt_pk_bf16_f32 v10, v0, s0
	v_or_b32_e32 v0, v32, v14
	v_lshlrev_b32_e32 v0, 1, v0
	v_lshl_add_u64 v[20:21], v[34:35], 0, v[0:1]
	v_cmp_ge_u32_e64 s[2:3], v37, v18
	global_store_short v[20:21], v10, off
	s_and_saveexec_b64 s[4:5], s[2:3]
	s_cbranch_execz .LBB0_1100
	v_mov_b32_e32 v0, v248
	v_mov_b32_e32 v10, v219
	v_sub_f32_e32 v0, v0, v10
	v_mul_f32_e32 v0, 0x3fb8aa3b, v0
	v_exp_f32_e32 v11, v0
.LBB0_1100:
	s_or_b64 exec, exec, s[4:5]
	v_cmp_gt_u32_e64 s[2:3], v37, v18
	v_mov_b32_e32 v10, 0
	v_mov_b32_e32 v0, 0
	s_and_saveexec_b64 s[4:5], s[2:3]
	s_cbranch_execz .LBB0_1102
	v_mov_b32_e32 v0, v250
	v_mul_f32_e32 v0, v17, v0
	v_mul_f32_e32 v0, v11, v0
.LBB0_1102:
	s_or_b64 exec, exec, s[4:5]
	ds_write_b32 v95, v0 offset:34940
	v_mul_f32_e32 v0, v13, v11
	v_cvt_pk_bf16_f32 v11, v0, s0
	v_or_b32_e32 v0, v33, v14
	v_lshlrev_b32_e32 v0, 1, v0
	v_lshl_add_u64 v[12:13], v[34:35], 0, v[0:1]
	global_store_short v[12:13], v11, off
	v_cmp_ge_u32_e64 s[2:3], v112, v36
	ds_read_b32 v244, v110 offset:52480
	s_waitcnt lgkmcnt(0)
	s_and_saveexec_b64 s[4:5], s[2:3]
	s_cbranch_execz .LBB0_1104
	v_mov_b32_e32 v0, v251
	v_mov_b32_e32 v10, v244
	v_sub_f32_e32 v0, v0, v10
	v_mul_f32_e32 v0, 0x3fb8aa3b, v0
	v_exp_f32_e32 v10, v0
.LBB0_1104:
	s_or_b64 exec, exec, s[4:5]
	v_cmp_gt_u32_e64 s[2:3], v112, v36
	v_mov_b32_e32 v11, 0
	v_mov_b32_e32 v0, 0
	s_and_saveexec_b64 s[4:5], s[2:3]
	s_cbranch_execz .LBB0_1106
	v_mov_b32_e32 v0, v214
	v_mul_f32_e32 v0, v6, v0
	v_mul_f32_e32 v0, v10, v0
.LBB0_1106:
	s_or_b64 exec, exec, s[4:5]
	v_lshlrev_b32_e32 v6, 1, v36
	v_and_b32_e32 v12, 3, v36
	v_and_or_b32 v6, v6, 24, v12
	ds_write_b32 v111, v0 offset:34876
	v_mul_f32_e32 v0, v2, v10
	v_cvt_pk_bf16_f32 v2, v0, s0
	v_or_b32_e32 v0, v30, v6
	v_lshlrev_b32_e32 v0, 1, v0
	v_lshl_add_u64 v[12:13], v[34:35], 0, v[0:1]
	v_cmp_ge_u32_e64 s[2:3], v26, v36
	global_store_short v[12:13], v2, off
	s_and_saveexec_b64 s[4:5], s[2:3]
	s_cbranch_execz .LBB0_1108
	v_mov_b32_e32 v0, v215
	v_mov_b32_e32 v2, v244
	v_sub_f32_e32 v0, v0, v2
	v_mul_f32_e32 v0, 0x3fb8aa3b, v0
	v_exp_f32_e32 v11, v0
.LBB0_1108:
	s_or_b64 exec, exec, s[4:5]
	v_cmp_gt_u32_e64 s[2:3], v26, v36
	v_mov_b32_e32 v2, 0
	v_mov_b32_e32 v0, 0
	s_and_saveexec_b64 s[4:5], s[2:3]
	s_cbranch_execz .LBB0_1110
	v_mov_b32_e32 v0, v216
	v_mul_f32_e32 v0, v7, v0
	v_mul_f32_e32 v0, v11, v0
.LBB0_1110:
	s_or_b64 exec, exec, s[4:5]
	ds_write_b32 v113, v0 offset:34876
	v_mul_f32_e32 v0, v3, v11
	v_cvt_pk_bf16_f32 v3, v0, s0
	v_or_b32_e32 v0, v31, v6
	v_lshlrev_b32_e32 v0, 1, v0
	v_lshl_add_u64 v[10:11], v[34:35], 0, v[0:1]
	v_cmp_ge_u32_e64 s[2:3], v27, v36
	global_store_short v[10:11], v3, off
	s_and_saveexec_b64 s[4:5], s[2:3]
	s_cbranch_execz .LBB0_1112
	v_mov_b32_e32 v0, v217
	v_mov_b32_e32 v2, v244
	v_sub_f32_e32 v0, v0, v2
	v_mul_f32_e32 v0, 0x3fb8aa3b, v0
	v_exp_f32_e32 v2, v0
.LBB0_1112:
	s_or_b64 exec, exec, s[4:5]
	v_cmp_gt_u32_e64 s[2:3], v27, v36
	v_mov_b32_e32 v3, 0
	v_mov_b32_e32 v0, 0
	s_and_saveexec_b64 s[4:5], s[2:3]
	s_cbranch_execz .LBB0_1114
	v_mov_b32_e32 v0, v218
	v_mul_f32_e32 v0, v8, v0
	v_mul_f32_e32 v0, v2, v0
.LBB0_1114:
	s_or_b64 exec, exec, s[4:5]
	ds_write_b32 v109, v0 offset:34876
	v_mul_f32_e32 v0, v4, v2
	v_cvt_pk_bf16_f32 v2, v0, s0
	v_or_b32_e32 v0, v32, v6
	v_lshlrev_b32_e32 v0, 1, v0
	v_lshl_add_u64 v[10:11], v[34:35], 0, v[0:1]
	v_cmp_ge_u32_e64 s[2:3], v37, v36
	global_store_short v[10:11], v2, off
	s_and_saveexec_b64 s[4:5], s[2:3]
	s_cbranch_execz .LBB0_1116
	v_mov_b32_e32 v0, v248
	v_mov_b32_e32 v2, v244
	v_sub_f32_e32 v0, v0, v2
	v_mul_f32_e32 v0, 0x3fb8aa3b, v0
	v_exp_f32_e32 v3, v0
.LBB0_1116:
	s_or_b64 exec, exec, s[4:5]
	v_cmp_gt_u32_e64 s[2:3], v37, v36
	v_mov_b32_e32 v0, 0
	s_and_saveexec_b64 s[4:5], s[2:3]
	s_cbranch_execz .LBB0_1118
	v_mov_b32_e32 v0, v250
	v_mul_f32_e32 v0, v9, v0
	v_mul_f32_e32 v0, v3, v0

.LBB0_1358:
	s_branch .LBB0_1361
.LBB0_1359:
	v_and_b32_e32 v24, 63, v201
	v_mov_b32_e32 v53, 0
	v_lshlrev_b32_e32 v52, 4, v201
	v_and_b32_e32 v52, 0xf0, v52
	v_lshl_add_u64 v[54:55], s[2:3], 0, v[52:53]
	v_bfe_u32 v52, v201, 6, 2
	v_add_u32_e32 v50, v4, v52
	v_ashrrev_i32_e32 v51, 31, v50
	v_lshlrev_b64 v[36:37], 10, v[50:51]
	v_lshl_add_u64 v[36:37], s[0:1], 0, v[36:37]
	v_lshlrev_b32_e32 v52, 4, v24
	v_lshl_add_u64 v[40:41], v[36:37], 0, v[52:53]
	v_lshlrev_b64 v[36:37], 9, v[50:51]
	v_lshl_add_u64 v[36:37], s[4:5], 0, v[36:37]
	v_lshlrev_b32_e32 v52, 3, v24
	v_lshl_add_u64 v[36:37], v[36:37], 0, v[52:53]
	global_load_dwordx2 v[48:49], v[36:37], off
	global_load_dwordx4 v[36:39], v[40:41], off
	v_add_co_u32_e32 v40, vcc, s90, v40
	s_nop 1
	v_addc_co_u32_e32 v41, vcc, 0, v41, vcc
	global_load_dwordx4 v[40:43], v[40:41], off
	global_load_dwordx4 v[44:47], v[54:55], off
	s_waitcnt vmcnt(0)
	s_branch .Le_enter
.Le_top:
	s_waitcnt vmcnt(3)
.Le_enter:
	v_mov_b64_e32 v[18:19], v[48:49]
	v_mov_b64_e32 v[6:7], v[36:37]
	v_mov_b64_e32 v[8:9], v[38:39]
	v_mov_b64_e32 v[10:11], v[40:41]
	v_mov_b64_e32 v[12:13], v[42:43]
	v_mov_b64_e32 v[14:15], v[44:45]
	v_mov_b64_e32 v[16:17], v[46:47]
	v_mov_b64_e32 v[2:3], v[50:51]
	v_readlane_b32 s12, v254, 1
	s_nop 3
	s_add_i32 s16, s16, s12
	v_add_u32_e32 v4, s40, v4
	v_readlane_b32 s13, v254, 2
	s_cmpk_gt_i32 s16, 0x10ff
	s_cbranch_scc1 .Le_nonext
	v_bfe_u32 v52, v201, 6, 2
	v_add_u32_e32 v50, v4, v52
	v_ashrrev_i32_e32 v51, 31, v50
	v_lshlrev_b64 v[36:37], 10, v[50:51]
	v_lshl_add_u64 v[36:37], s[0:1], 0, v[36:37]
	v_lshlrev_b32_e32 v52, 4, v24
	v_lshl_add_u64 v[40:41], v[36:37], 0, v[52:53]
	v_lshlrev_b64 v[36:37], 9, v[50:51]
	v_lshl_add_u64 v[36:37], s[4:5], 0, v[36:37]
	v_lshlrev_b32_e32 v52, 3, v24
	v_lshl_add_u64 v[36:37], v[36:37], 0, v[52:53]
	global_load_dwordx2 v[48:49], v[36:37], off
	global_load_dwordx4 v[36:39], v[40:41], off
	v_add_co_u32_e32 v40, vcc, s90, v40
	s_nop 1
	v_addc_co_u32_e32 v41, vcc, 0, v41, vcc
	global_load_dwordx4 v[40:43], v[40:41], off
	global_load_dwordx4 v[44:47], v[54:55], off
.Le_nonext:
	v_and_b32_e32 v20, 64, v208
	v_xor_b32_e32 v5, 1, v208
	v_lshlrev_b32_e32 v0, 3, v24
	v_add_u32_e32 v20, 64, v20
	v_cmp_lt_i32_e32 vcc, v5, v20
	v_xor_b32_e32 v21, 2, v208
	v_xor_b32_e32 v22, 4, v208
	v_cndmask_b32_e32 v5, v208, v5, vcc
	v_lshlrev_b32_e32 v5, 2, v5
	v_cmp_lt_i32_e32 vcc, v21, v20
	v_xor_b32_e32 v23, 8, v208
	v_pk_add_f32 v[6:7], v[6:7], v[10:11]
	v_pk_add_f32 v[8:9], v[8:9], v[12:13]
	v_pk_mul_f32 v[12:13], v[6:7], v[6:7]
	v_pk_mul_f32 v[10:11], v[8:9], v[8:9]
	v_add_f32_e32 v12, v12, v13
	v_add_f32_e32 v10, v12, v10
	v_add_f32_e32 v10, v10, v11
	ds_bpermute_b32 v5, v5, v10
	v_cndmask_b32_e32 v21, v208, v21, vcc
	v_lshlrev_b32_e32 v25, 2, v21
	v_cmp_lt_i32_e32 vcc, v22, v20
	s_waitcnt lgkmcnt(0)
	v_add_f32_e32 v5, v10, v5
	ds_bpermute_b32 v10, v25, v5
	v_cndmask_b32_e32 v22, v208, v22, vcc
	v_lshlrev_b32_e32 v26, 2, v22
	v_cmp_lt_i32_e32 vcc, v23, v20
	v_lshlrev_b32_e32 v22, 16, v18
	s_waitcnt lgkmcnt(0)
	v_add_f32_e32 v5, v5, v10
	ds_bpermute_b32 v10, v26, v5
	v_cndmask_b32_e32 v20, v208, v23, vcc
	v_lshlrev_b32_e32 v27, 2, v20
	v_and_b32_e32 v23, 0xffff0000, v18
	v_lshlrev_b32_e32 v18, 16, v19
	s_waitcnt lgkmcnt(0)
	v_add_f32_e32 v5, v5, v10
	v_and_b32_e32 v19, 0xffff0000, v19
	ds_bpermute_b32 v26, v27, v5
	v_mul_f32_e32 v11, 0xbfb8aa3b, v22
	v_mul_f32_e32 v12, 0xbfb8aa3b, v23
	v_mul_f32_e32 v13, 0xbfb8aa3b, v18
	v_mul_f32_e32 v28, 0xbfb8aa3b, v19
	v_exp_f32_e32 v11, v11
	v_exp_f32_e32 v12, v12
	v_exp_f32_e32 v13, v13
	v_exp_f32_e32 v25, v28
	s_waitcnt lgkmcnt(0)
	v_add_f32_e32 v5, v5, v26
	v_add_f32_e32 v11, 1.0, v11
	v_add_f32_e32 v12, 1.0, v12
	v_add_f32_e32 v13, 1.0, v13
	v_add_f32_e32 v25, 1.0, v25
	v_fmamk_f32 v5, v5, 0x3c800000, v206
	v_rcp_f32_e32 v10, v11
	v_rcp_f32_e32 v11, v12
	v_rcp_f32_e32 v12, v13
	v_rcp_f32_e32 v13, v25
	v_mul_f32_e32 v25, 0x4b800000, v5
	v_cmp_gt_f32_e32 vcc, s35, v5
	v_lshlrev_b64 v[20:21], 11, v[2:3]
	v_lshl_add_u64 v[20:21], s[6:7], 0, v[20:21]
	v_cndmask_b32_e32 v5, v5, v25, vcc
	v_rsq_f32_e32 v5, v5
	v_lshl_add_u64 v[20:21], v[20:21], 0, v[0:1]
	v_pk_mul_f32 v[10:11], v[10:11], v[22:23]
	v_pk_mul_f32 v[12:13], v[12:13], v[18:19]
	v_mul_f32_e32 v0, 0x45800000, v5
	v_cndmask_b32_e32 v0, v5, v0, vcc
	v_pk_mul_f32 v[6:7], v[6:7], v[0:1] op_sel_hi:[1,0]
	v_pk_mul_f32 v[8:9], v[8:9], v[0:1] op_sel_hi:[1,0]
	v_pk_mul_f32 v[6:7], v[14:15], v[6:7]
	v_pk_mul_f32 v[8:9], v[16:17], v[8:9]
	v_pk_mul_f32 v[6:7], v[6:7], v[10:11]
	v_pk_mul_f32 v[8:9], v[8:9], v[12:13]
	v_cvt_pk_bf16_f32 v6, v6, v7
	v_cvt_pk_bf16_f32 v7, v8, v9
	v_cmp_eq_u32_e32 vcc, 0, v24
	global_store_dwordx2 v[20:21], v[6:7], off
	s_and_saveexec_b64 s[12:13], vcc
	s_cbranch_execz .Le_skipz
	v_lshlrev_b64 v[2:3], 2, v[2:3]
	v_lshl_add_u64 v[6:7], s[8:9], 0, v[2:3]
	v_lshl_add_u64 v[2:3], s[10:11], 0, v[2:3]
	global_store_dword v[6:7], v1, off
	global_store_dword v[2:3], v1, off
.Le_skipz:
	s_or_b64 exec, exec, s[12:13]
	v_readlane_b32 s12, v254, 1
	v_readlane_b32 s13, v254, 2
	s_cmpk_gt_i32 s16, 0x10ff
	s_cbranch_scc0 .Le_top
	s_branch .LBB0_1361
